# ring protocol with one workgroup barrier per chunk: loaders run 14 chunks ahead with 12 LDS-DMA chunks in flight instead of 9
# speedup vs baseline: 1.0062x; 1.0062x over previous
; #define SP_BAR() asm volatile("s_waitcnt lgkmcnt(0)\n\ts_barrier" ::: "memory")
; #define SP_WAIT() asm volatile("s_waitcnt vmcnt(36)" ::: "memory")
; __device__ __forceinline__ void p3_rwkv_state(Frame& F, const Args& a) {
;     ...
;     if (loader) {
;         DmaPtrs P; rw_dma_init(a, P, head, ib, lw, lane);
;         for (int n = 0; n < SP_D; ++n) rw_dma_issue(P, lw, lane, lds0 + (unsigned)(n % SP_R) * SP_SLOT);
;         SP_WAIT();
;         SP_BAR();
;         for (int n = 0; n < NC; n += 2) {
;             if (n + SP_D + 1 < NC) { rw_dma_issue(P, lw, lane, lds0 + (unsigned)((n + SP_D) % SP_R) * SP_SLOT); rw_dma_issue(P, lw, lane, lds0 + (unsigned)((n + SP_D + 1) % SP_R) * SP_SLOT); SP_WAIT(); }
;             else asm volatile("s_waitcnt vmcnt(0)" ::: "memory");
;             SP_BAR();
;         }
.Lscan_ldbig_pro:
	s_add_i32 s16, s15, s14
	s_mov_b32 m0, s16
	s_add_i32 s15, s15, 0x2800
	global_load_lds_dwordx4 v[2:3], off
	global_load_lds_dwordx4 v[2:3], off offset:1024
	s_cmp_eq_u32 s15, 0x25800
	s_cselect_b32 s15, 0, s15
	v_lshl_add_u64 v[2:3], v[2:3], 0, s[6:7]
	s_add_i32 s18, s18, 1
	s_cmp_lt_u32 s18, 14
	s_cbranch_scc1 .Lscan_ldbig_pro
	s_waitcnt vmcnt(24)
	s_barrier
	s_mov_b32 s18, 0
	s_movk_i32 s17, 0x200
.Lscan_ldbig_loop:
	s_cmpk_gt_u32 s18, 0x3f1
	s_cbranch_scc1 .Lscan_ldbig_tail
.Lscan_ldbig_chk:
	s_add_i32 s24, s18, 14
	s_cmp_lt_u32 s24, s17
	s_cbranch_scc1 .Lscan_ldbig_go
	v_add_u32_e32 v12, s17, v76
	v_lshlrev_b32_e32 v13, 2, v12
	v_add_u32_e32 v13, 0x8000, v13
	global_load_dword v13, v13, s[90:91] sc1
	s_movk_i32 s24, 0x3ff
	s_waitcnt vmcnt(0)
	v_cmp_ne_u32_e64 s[20:21], 0, v13
	v_cmp_lt_u32_e64 s[22:23], s24, v12
	s_nop 1
	s_or_b64 s[20:21], s[20:21], s[22:23]
	s_not_b64 s[20:21], s[20:21]
	s_ff1_i32_b64 s24, s[20:21]
	s_cmp_eq_u32 s24, -1
	s_cselect_b32 s24, 64, s24
	s_add_i32 s17, s17, s24
	buffer_inv sc1
	s_waitcnt vmcnt(0)
	s_cmp_lg_u32 s24, 0
	s_cbranch_scc1 .Lscan_ldbig_chk
	s_sleep 8
	s_branch .Lscan_ldbig_chk
.Lscan_ldbig_go:
	s_add_i32 s16, s15, s14
	s_mov_b32 m0, s16
	s_add_i32 s15, s15, 0x2800
	global_load_lds_dwordx4 v[2:3], off
	global_load_lds_dwordx4 v[2:3], off offset:1024
	s_cmp_eq_u32 s15, 0x25800
	s_cselect_b32 s15, 0, s15
	v_lshl_add_u64 v[2:3], v[2:3], 0, s[6:7]
	s_waitcnt vmcnt(24)
	s_branch .Lscan_ldbig_bar

; #define SP_BAR() asm volatile("s_waitcnt lgkmcnt(0)\n\ts_barrier" ::: "memory")
; #define SP_WAIT() asm volatile("s_waitcnt vmcnt(36)" ::: "memory")
; __device__ __forceinline__ void p3_rwkv_state(Frame& F, const Args& a) {
;     ...
;         for (int n = 0; n < NC; n += 2) {
;             if (n + SP_D + 1 < NC) { rw_dma_issue(P, lw, lane, lds0 + (unsigned)((n + SP_D) % SP_R) * SP_SLOT); rw_dma_issue(P, lw, lane, lds0 + (unsigned)((n + SP_D + 1) % SP_R) * SP_SLOT); SP_WAIT(); }
;             else asm volatile("s_waitcnt vmcnt(0)" ::: "memory");
;             SP_BAR();
;         }
.Lscan_ldbig_bar:
	s_barrier
	s_add_i32 s18, s18, 1
	s_cmpk_lt_u32 s18, 0x400
	s_cbranch_scc1 .Lscan_ldbig_loop
	s_mov_b32 m0, s19
	s_branch .LBB0_456

; #define SP_BAR() asm volatile("s_waitcnt lgkmcnt(0)\n\ts_barrier" ::: "memory")
; #define SP_WAIT() asm volatile("s_waitcnt vmcnt(36)" ::: "memory")
; __device__ __forceinline__ void p3_rwkv_state(Frame& F, const Args& a) {
;     ...
;     if (loader) {
;         DmaPtrs P; rw_dma_init(a, P, head, ib, lw, lane);
;         for (int n = 0; n < SP_D; ++n) rw_dma_issue(P, lw, lane, lds0 + (unsigned)(n % SP_R) * SP_SLOT);
;         SP_WAIT();
;         SP_BAR();
.Lscan_ldsmall_pro:
	s_add_i32 s16, s15, 0x2000
	s_mov_b32 m0, s16
	s_mov_b32 exec_hi, 0
	s_add_i32 s15, s15, 0x2800
	global_load_lds_dwordx4 v[2:3], off
	global_load_lds_dwordx4 v[4:5], off offset:512
	global_load_lds_dwordx4 v[6:7], off offset:1024
	s_mov_b32 exec_lo, 0xffff
	s_cmp_eq_u32 s15, 0x25800
	global_load_lds_dwordx4 v[8:9], off offset:1536
	s_mov_b64 exec, -1
	s_cselect_b32 s15, 0, s15
	v_lshl_add_u64 v[2:3], v[2:3], 0, s[6:7]
	v_lshl_add_u64 v[4:5], v[4:5], 0, s[6:7]
	v_lshl_add_u64 v[6:7], v[6:7], 0, s[6:7]
	v_lshl_add_u64 v[8:9], v[8:9], 0, s[10:11]
	s_add_i32 s18, s18, 1
	s_cmp_lt_u32 s18, 14
	s_cbranch_scc1 .Lscan_ldsmall_pro
	s_waitcnt vmcnt(48)
	s_barrier
	s_mov_b32 s18, 0
	s_movk_i32 s17, 0x200

; #define SP_WAIT() asm volatile("s_waitcnt vmcnt(36)" ::: "memory")
; __device__ __forceinline__ void p3_rwkv_state(Frame& F, const Args& a) {
;     ...
;         for (int n = 0; n < NC; n += 2) {
;             if (n + SP_D + 1 < NC) { rw_dma_issue(P, lw, lane, lds0 + (unsigned)((n + SP_D) % SP_R) * SP_SLOT); rw_dma_issue(P, lw, lane, lds0 + (unsigned)((n + SP_D + 1) % SP_R) * SP_SLOT); SP_WAIT(); }
;             else asm volatile("s_waitcnt vmcnt(0)" ::: "memory");
.Lscan_ldsmall_go:
	s_add_i32 s16, s15, 0x2000
	s_mov_b32 m0, s16
	s_mov_b32 exec_hi, 0
	s_add_i32 s15, s15, 0x2800
	global_load_lds_dwordx4 v[2:3], off
	global_load_lds_dwordx4 v[4:5], off offset:512
	global_load_lds_dwordx4 v[6:7], off offset:1024
	s_mov_b32 exec_lo, 0xffff
	s_cmp_eq_u32 s15, 0x25800
	global_load_lds_dwordx4 v[8:9], off offset:1536
	s_mov_b64 exec, -1
	s_cselect_b32 s15, 0, s15
	v_lshl_add_u64 v[2:3], v[2:3], 0, s[6:7]
	v_lshl_add_u64 v[4:5], v[4:5], 0, s[6:7]
	v_lshl_add_u64 v[6:7], v[6:7], 0, s[6:7]
	v_lshl_add_u64 v[8:9], v[8:9], 0, s[10:11]
	s_waitcnt vmcnt(48)
	s_branch .Lscan_ldsmall_bar

; #define SP_BAR() asm volatile("s_waitcnt lgkmcnt(0)\n\ts_barrier" ::: "memory")
; __device__ __forceinline__ void p3_rwkv_state(Frame& F, const Args& a) {
;     ...
;     } else {
;         for (int n = 0; n < NC / 2 + 1; ++n) SP_BAR();
;     }
.Lscan_idle:
	s_movk_i32 s1, 0x401

; __device__ __forceinline__ void p3_rwkv_state(Frame& F, const Args& a) {
;     ...
;         for (int n = 0; n < NC; n += 2) { SP_STEP(C, N, n); SP_STEP(N, C, n + 1); }
.Lscan_loop:
	v_add_u32_e32 v80, s10, v77
	v_add_u32_e32 v81, s10, v78
	v_add_u32_e32 v82, s10, v79
	s_add_i32 s10, s10, 0x2800
	s_cmp_eq_u32 s10, 0x25800
	s_cselect_b32 s10, 0, s10
	v_mfma_f32_16x16x32_bf16 v[24:27], v[32:35], v[16:19], v[24:27]
	v_mfma_f32_16x16x32_bf16 v[28:31], v[40:43], v[16:19], v[28:31]
	v_mfma_f32_16x16x32_bf16 v[24:27], v[36:39], v[20:23], v[24:27]
	v_mfma_f32_16x16x32_bf16 v[28:31], v[44:47], v[20:23], v[28:31]
	ds_read_b128 v[32:35], v80
	ds_read_b128 v[36:39], v80 offset:1024
	ds_read_b128 v[40:43], v80 offset:2048
	ds_read_b128 v[44:47], v80 offset:3072
	ds_read2st64_b64 v[96:99], v81 offset0:16 offset1:17
	s_waitcnt lgkmcnt(10)
	v_mul_f32_e32 v0, v64, v0
	v_mul_f32_e32 v1, v65, v1
	v_mul_f32_e32 v2, v66, v2
	v_mul_f32_e32 v3, v67, v3
	v_mul_f32_e32 v4, v68, v4
	v_mul_f32_e32 v5, v69, v5
	v_mul_f32_e32 v6, v70, v6
	v_mul_f32_e32 v7, v71, v7
	v_mul_f32_e32 v8, v72, v8
	v_mul_f32_e32 v9, v73, v9
	v_mul_f32_e32 v10, v74, v10
	v_mul_f32_e32 v11, v75, v11
	v_mul_f32_e32 v12, v88, v12
	v_mul_f32_e32 v13, v89, v13
	v_mul_f32_e32 v14, v90, v14
	v_mul_f32_e32 v15, v91, v15
	ds_read_b128 v[64:67], v82 offset:9728
	ds_read_b128 v[68:71], v82 offset:9744
	ds_read_b128 v[72:75], v82 offset:9760
	ds_read_b128 v[88:91], v82 offset:9776
	v_cvt_pk_bf16_f32 v94, v24, v25
	v_cvt_pk_bf16_f32 v95, v26, v27
	s_waitcnt lgkmcnt(9)
	s_nop 1
	v_mfma_f32_16x16x32_bf16 v[0:3], v[48:51], v[92:95], v[0:3]
	v_mfma_f32_16x16x32_bf16 v[4:7], v[52:55], v[92:95], v[4:7]
	v_mfma_f32_16x16x32_bf16 v[8:11], v[56:59], v[92:95], v[8:11]
	v_mfma_f32_16x16x32_bf16 v[12:15], v[60:63], v[92:95], v[12:15]
	v_cvt_pk_bf16_f32 v84, v28, v29
	v_cvt_pk_bf16_f32 v85, v30, v31
	ds_read2st64_b64 v[48:51], v81 offset0:12 offset1:8
	ds_read2st64_b64 v[52:55], v81 offset0:13 offset1:9
	ds_read2st64_b64 v[56:59], v81 offset0:14 offset1:10
	ds_read2st64_b64 v[60:63], v81 offset0:15 offset1:11
	ds_read_b64 v[92:93], v81 offset:9216
	global_store_short v83, v84, s[8:9] offset:-4096
	global_store_short_d16_hi v83, v84, s[8:9] offset:-2048
	global_store_short v83, v85, s[8:9]
	global_store_short_d16_hi v83, v85, s[8:9] offset:2048
	s_add_u32 s8, s8, 0x8000
	s_addc_u32 s9, s9, 0
	s_waitcnt lgkmcnt(9)
	v_lshlrev_b32_e32 v24, 16, v96
	v_and_b32_e32 v25, 0xffff0000, v96
	v_lshlrev_b32_e32 v26, 16, v97
	v_and_b32_e32 v27, 0xffff0000, v97
	v_lshlrev_b32_e32 v28, 16, v98
	v_and_b32_e32 v29, 0xffff0000, v98
	v_lshlrev_b32_e32 v30, 16, v99
	v_and_b32_e32 v31, 0xffff0000, v99
	v_cvt_pk_bf16_f32 v16, v0, v1
	v_cvt_pk_bf16_f32 v17, v2, v3
	v_cvt_pk_bf16_f32 v18, v4, v5
	v_cvt_pk_bf16_f32 v19, v6, v7
	v_cvt_pk_bf16_f32 v20, v8, v9
	v_cvt_pk_bf16_f32 v21, v10, v11
	v_cvt_pk_bf16_f32 v22, v12, v13
	v_cvt_pk_bf16_f32 v23, v14, v15
	s_barrier
	s_add_i32 s11, s11, 1
	s_cmpk_lt_u32 s11, 0x400
	s_cbranch_scc1 .Lscan_loop
	s_branch .LBB0_456
